# RG-LRU gate GEMM: skip the all-zero k-tiles of the block-diagonal weight (K range restricted per column tile), bit-identical
# speedup vs baseline: 1.0109x; 1.0064x over previous
; #define TIDX tid_opaque()
; #define PG8_STAGE(bufoff, gbase, voff) do { _Pragma("unroll") for (int _i = 0; _i < 2; ++_i) \
;         __builtin_amdgcn_global_load_lds((const unsigned*)((const char*)(gbase) + (voff)[_i]), (LAS unsigned*)(lds + (bufoff) + ldsw + _i * 8192), 16, 0, 0); } while (0)
; #define PG8_WAIT_V(n) asm volatile("s_waitcnt vmcnt(" #n ")" ::: "memory")
; #define PG8_BAR __builtin_amdgcn_s_barrier()
; template <class Epi>
; __device__ __forceinline__ void gemm_phase(LAS unsigned char* lds, const Gemm g, const StaticOrder& S, const Epi& E, const bool perm) {
;     const int tid = TIDX, wid = __builtin_amdgcn_readfirstlane(tid >> 6), lane = tid & 63, wr = wid >> 2, wc = wid & 3, fr = lane & 15, fq = lane >> 4;
;     const int K = g.K, nt = K / BK;
;     unsigned voffA[2], voffB[2];
; #pragma unroll
;     for (int i = 0; i < 2; ++i) { int R, C; stage_rc(tid * 16 + i * 8192, R, C); const int Rb = perm ? ((R & ~31) + perm32(R & 31)) : R;
;         voffA[i] = (unsigned)(R * K + C) * 2u; voffB[i] = (unsigned)(Rb * K + C) * 2u; }
;     const size_t kstep = (size_t)(BK * 2);
;     const size_t hstep = (size_t)HALF * K * 2;
;     const size_t tstep = 2 * hstep;
;     const unsigned ldsw = (unsigned)wid * 1024u;
;     const int aoff = lds_byte(wr * 64 + fr, fq * 8), boff = lds_byte(wc * 32 + fr, fq * 8);
;     ...
;     Unit cur, nxt; int ui = 0;
;     if (!S.next(0, cur)) return;
;     f32x4 acc[2][2][4][2];
; #pragma unroll
;     for (int a = 0; a < 2; ++a)
; #pragma unroll
;         for (int b = 0; b < 2; ++b)
; #pragma unroll
;             for (int m = 0; m < 4; ++m)
; #pragma unroll
;                 for (int n = 0; n < 2; ++n) acc[a][b][m][n] = (f32x4){0.f, 0.f, 0.f, 0.f};
;     bf16x8 At[4][2], B0[2][2], B1[2][2];
;     const char* cA = (const char*)g.A + (size_t)cur.pm * tstep; const char* cB = (const char*)g.Bt + (size_t)cur.pn * tstep;
;     PG8_STAGE(PG8_SB(0, 0), cB, voffB); PG8_STAGE(PG8_SA(0, 0), cA, voffA); PG8_STAGE(PG8_SB(0, 1), cB + hstep, voffB); PG8_STAGE(PG8_SA(0, 1), cA + hstep, voffA);
;     if (wr == 1) PG8_BAR;
;     PG8_WAIT_V(4); PG8_BAR;
;     PG8_STAGE(PG8_SB(1, 0), cB + kstep, voffB); PG8_STAGE(PG8_SA(1, 0), cA + kstep, voffA); PG8_STAGE(PG8_SB(1, 1), cB + hstep + kstep, voffB);
;     PG8_WAIT_V(6); PG8_BAR;
.LBB0_450:
	s_and_b64 vcc, exec, s[0:1]
	s_cbranch_vccz .LBB0_766
	v_readlane_b32 s0, v255, 59
	s_ashr_i32 s9, s0, 6
	s_ashr_i32 s8, s0, 8
	s_lshl_b64 s[82:83], s[24:25], 9
	s_ashr_i32 s0, s46, 31
	s_mul_i32 s0, s82, s0
	s_mul_hi_u32 s1, s82, s46
	s_ashr_i32 s7, s70, 31
	v_mul_i32_i24_e32 v7, 64, v7
	s_add_i32 s0, s1, s0
	s_lshr_b32 s1, s24, 23
	s_mul_i32 s7, s82, s7
	s_mul_hi_u32 s11, s82, s70
	v_mov_b32_e32 v11, 1
	v_sub_u32_e32 v4, v4, v7
	s_mul_i32 s6, s1, s46
	s_add_i32 s7, s11, s7
	s_mul_i32 s1, s1, s70
	v_lshlrev_b32_e32 v9, 6, v9
	s_lshl_b64 s[80:81], s[24:25], 8
	s_lshl_b32 s31, s9, 10
	v_lshlrev_b32_e32 v2, 5, v2
	v_ashrrev_i16_sdwa v4, v11, sext(v4) dst_sel:DWORD dst_unused:UNUSED_PAD src0_sel:DWORD src1_sel:BYTE_0
	s_add_i32 s0, s0, s6
	s_add_i32 s7, s7, s1
	s_mul_i32 s1, s82, s70
	v_sub_u32_e32 v3, v3, v9
	v_and_b32_e32 v2, 32, v2
	v_bfe_i32 v4, v4, 0, 16
	s_add_u32 s22, s48, s1
	v_lshlrev_b32_e32 v1, 5, v1
	v_ashrrev_i16_sdwa v3, v11, sext(v3) dst_sel:DWORD dst_unused:UNUSED_PAD src0_sel:DWORD src1_sel:BYTE_0
	v_add_u32_e32 v7, v2, v4
	v_mul_lo_u32 v8, v8, s24
	s_addc_u32 s23, s49, s7
	s_add_i32 s36, s31, 0
	s_and_b32 s98, s70, 3
	s_lshl_b32 s98, s98, 8
	s_cmp_eq_u32 s5, 7
	s_cselect_b32 s98, s98, 0
	s_add_u32 s22, s22, s98
	s_addc_u32 s23, s23, 0
	v_and_b32_e32 v1, 32, v1
	v_bfe_i32 v3, v3, 0, 16
	v_add_lshl_u32 v212, v8, v7, 1
	s_add_i32 m0, s36, 0x10000
	v_add_u32_e32 v9, v1, v3
	v_mul_lo_u32 v10, v10, s24
	s_mul_i32 s6, s82, s46
	global_load_lds_dwordx4 v212, s[22:23]
	s_add_i32 m0, s36, 0x12000
	v_add_lshl_u32 v208, v10, v9, 1
	v_mul_lo_u32 v5, v5, s24
	s_add_u32 s6, s28, s6
	v_mul_lo_u32 v6, v6, s24
	v_add_lshl_u32 v210, v7, v5, 1
	global_load_lds_dwordx4 v208, s[22:23]
	s_addc_u32 s7, s29, s0
	s_add_u32 s6, s6, s98
	s_addc_u32 s7, s7, 0
	s_mov_b32 m0, s36
	s_add_i32 s37, s36, 0x2000
	v_add_lshl_u32 v206, v9, v6, 1
	global_load_lds_dwordx4 v210, s[6:7]
	s_mov_b32 m0, s37
	s_add_u32 s0, s22, s80
	global_load_lds_dwordx4 v206, s[6:7]
	s_addc_u32 s1, s23, s81
	s_add_i32 m0, s36, 0x14000
	s_nop 0
	global_load_lds_dwordx4 v212, s[0:1]
	s_add_i32 m0, s36, 0x16000
	s_add_u32 s12, s6, s80
	s_addc_u32 s13, s7, s81
	s_add_i32 s34, s36, 0x4000
	global_load_lds_dwordx4 v208, s[0:1]
	s_mov_b32 m0, s34
	s_add_i32 s35, s36, 0x6000
	global_load_lds_dwordx4 v210, s[12:13]
	s_mov_b32 m0, s35
	s_cmp_lg_u32 s8, 1
	global_load_lds_dwordx4 v206, s[12:13]
	s_cbranch_scc1 .LBB0_453
	s_barrier
.LBB0_453:
	v_mov_b32_e32 v213, v185
	v_lshl_add_u64 v[8:9], s[22:23], 0, v[212:213]
	v_mov_b32_e32 v209, v185
	v_lshl_add_u64 v[10:11], s[22:23], 0, v[208:209]
	v_mov_b32_e32 v211, v185
	s_add_i32 m0, s36, 0x18000
	v_lshl_add_u64 v[8:9], v[8:9], 0, s[74:75]
	v_lshl_add_u64 v[12:13], s[6:7], 0, v[210:211]
	v_mov_b32_e32 v207, v185
	s_waitcnt vmcnt(4)
	s_barrier
	global_load_lds_dwordx4 v[8:9], off
	v_lshl_add_u64 v[8:9], v[10:11], 0, s[74:75]
	s_add_i32 m0, s36, 0x1a000
	s_add_i32 s14, s36, 0x8000
	s_waitcnt lgkmcnt(0)
	v_lshl_add_u64 v[14:15], s[6:7], 0, v[206:207]
	global_load_lds_dwordx4 v[8:9], off
	v_lshl_add_u64 v[8:9], v[12:13], 0, s[74:75]
	s_mov_b32 m0, s14
	s_add_i32 s15, s36, 0xa000
	v_lshl_add_u64 v[16:17], s[0:1], 0, v[212:213]
	global_load_lds_dwordx4 v[8:9], off
	v_lshl_add_u64 v[8:9], v[14:15], 0, s[74:75]
	s_mov_b32 m0, s15
	v_lshl_add_u64 v[18:19], s[0:1], 0, v[208:209]
	global_load_lds_dwordx4 v[8:9], off
	s_add_i32 m0, s36, 0x1c000
	v_lshl_add_u64 v[8:9], v[16:17], 0, s[74:75]
	global_load_lds_dwordx4 v[8:9], off
	v_lshl_add_u64 v[8:9], v[18:19], 0, s[74:75]
	s_add_i32 m0, s36, 0x1e000
	v_bfe_u32 v7, v0, 4, 2
	global_load_lds_dwordx4 v[8:9], off
	v_and_b32_e32 v187, 15, v0
	v_lshlrev_b32_e32 v8, 4, v7
	v_lshlrev_b32_e32 v0, 2, v0
	s_and_b32 s64, s9, 3
	v_lshl_or_b32 v8, v187, 6, v8
	s_lshl_b32 s0, s8, 13
	v_and_b32_e32 v0, 32, v0
	v_bitop3_b32 v9, v8, s0, v0 bitop3:0xde
	s_lshl_b32 s0, s64, 12
	s_lshl_b32 s39, s10, 3
	v_bitop3_b32 v245, v8, s0, v0 bitop3:0xde
	v_cvt_f32_u32_e32 v0, s39
	s_lshl_b32 s0, s10, 4
	v_writelane_b32 v255, s0, 62
	s_sub_i32 s0, 0, s39
	v_rcp_iflag_f32_e32 v0, v0
	s_waitcnt vmcnt(6)
	s_lshr_b32 s65, s24, 6
	s_cmp_eq_u32 s5, 7
	s_cselect_b32 s65, 2, s65
	s_lshl_b32 s76, s8, 6
	v_mul_f32_e32 v0, 0x4f7ffffe, v0
	v_cvt_u32_f32_e32 v0, v0
	s_lshl_b32 s77, s64, 5
	v_or_b32_e32 v244, s76, v187
	s_add_i32 s27, s65, -2
	v_readfirstlane_b32 s1, v0
	s_mul_i32 s0, s0, s1
	v_add_u32_e32 v0, v5, v2
	s_mul_hi_u32 s0, s1, s0
	v_add_lshl_u32 v184, v0, v4, 1
	v_add_u32_e32 v0, v6, v1
	s_add_i32 s0, s1, s0
	v_lshl_add_u64 v[214:215], s[80:81], 0, v[184:185]
	v_add_lshl_u32 v184, v0, v3, 1
	v_lshl_or_b32 v246, v7, 3, s77
	s_mov_b32 s24, 0
	v_cmp_eq_u32_e64 s[8:9], 0, v7
	v_lshlrev_b32_e32 v247, 2, v7
	s_ashr_i32 s92, s30, 31
	s_mov_b32 s63, s25
	s_mov_b32 s59, s58
	s_mov_b32 s16, s58
	s_mov_b32 s17, s58
	v_writelane_b32 v255, s0, 63
	v_lshl_add_u64 v[216:217], s[80:81], 0, v[184:185]
	v_add_u32_e32 v248, 0, v9
	s_barrier
	s_branch .LBB0_455

; template <class Epi>
; __device__ __forceinline__ void gemm_phase(LAS unsigned char* lds, const Gemm g, const StaticOrder& S, const Epi& E, const bool perm) {
;     ...
;         const bool has_next = S.next(ui + 1, nxt);
;         const char* nA = has_next ? (const char*)g.A + (size_t)nxt.pm * tstep : cA; const char* nB = has_next ? (const char*)g.Bt + (size_t)nxt.pn * tstep : cB;
.LBB0_457:
	v_cndmask_b32_e64 v0, 0, 1, s[0:1]
	v_cmp_ne_u32_e64 s[12:13], 1, v0
	s_andn2_b64 vcc, exec, s[0:1]
	s_mov_b64 s[0:1], s[6:7]
	s_cbranch_vccnz .LBB0_459
	s_ashr_i32 s0, s50, 31
	s_mul_hi_u32 s1, s82, s50
	s_mul_i32 s0, s82, s0
	s_add_i32 s0, s1, s0
	s_mul_i32 s1, s83, s50
	s_add_i32 s1, s0, s1
	s_mul_i32 s0, s82, s50
	s_add_u32 s0, s28, s0
	s_addc_u32 s1, s29, s1
	s_and_b32 s98, s66, 3
	s_lshl_b32 s98, s98, 8
	s_cmp_eq_u32 s5, 7
	s_cselect_b32 s98, s98, 0
	s_add_u32 s0, s0, s98
	s_addc_u32 s1, s1, 0
.LBB0_459:
	s_and_b64 vcc, exec, s[12:13]
	s_mov_b64 s[12:13], s[22:23]
	s_cbranch_vccnz .LBB0_461
	s_ashr_i32 s12, s66, 31
	s_mul_hi_u32 s13, s82, s66
	s_mul_i32 s12, s82, s12
	s_add_i32 s12, s13, s12
	s_mul_i32 s13, s83, s66
	s_add_i32 s13, s12, s13
	s_mul_i32 s12, s82, s66
	s_add_u32 s12, s48, s12
	s_addc_u32 s13, s49, s13
	s_and_b32 s98, s66, 3
	s_lshl_b32 s98, s98, 8
	s_cmp_eq_u32 s5, 7
	s_cselect_b32 s98, s98, 0
	s_add_u32 s12, s12, s98
	s_addc_u32 s13, s13, 0

; __global__ void __launch_bounds__(512, 2) fwd_megakernel(Params p) {
	.amdhsa_kernel _Z14fwd_megakernel6Params
		.amdhsa_group_segment_fixed_size 0
		.amdhsa_private_segment_fixed_size 0
		.amdhsa_kernarg_size 568
		.amdhsa_user_sgpr_count 2
		.amdhsa_user_sgpr_dispatch_ptr 0
		.amdhsa_user_sgpr_queue_ptr 0
		.amdhsa_user_sgpr_kernarg_segment_ptr 1
		.amdhsa_user_sgpr_dispatch_id 0
		.amdhsa_user_sgpr_kernarg_preload_length 0
		.amdhsa_user_sgpr_kernarg_preload_offset 0
		.amdhsa_user_sgpr_private_segment_size 0
		.amdhsa_uses_dynamic_stack 0
		.amdhsa_enable_private_segment 0
		.amdhsa_system_sgpr_workgroup_id_x 1
		.amdhsa_system_sgpr_workgroup_id_y 0
		.amdhsa_system_sgpr_workgroup_id_z 0
		.amdhsa_system_sgpr_workgroup_info 0
		.amdhsa_system_vgpr_workitem_id 2
		.amdhsa_next_free_vgpr 256
		.amdhsa_next_free_sgpr 102
		.amdhsa_accum_offset 256
		.amdhsa_reserve_vcc 1
		.amdhsa_float_round_mode_32 0
		.amdhsa_float_round_mode_16_64 0
		.amdhsa_float_denorm_mode_32 3
		.amdhsa_float_denorm_mode_16_64 3
		.amdhsa_dx10_clamp 1
		.amdhsa_ieee_mode 1
		.amdhsa_fp16_overflow 0
		.amdhsa_tg_split 0
		.amdhsa_exception_fp_ieee_invalid_op 0
		.amdhsa_exception_fp_denorm_src 0
		.amdhsa_exception_fp_ieee_div_zero 0
		.amdhsa_exception_fp_ieee_overflow 0
		.amdhsa_exception_fp_ieee_underflow 0
		.amdhsa_exception_fp_ieee_inexact 0
		.amdhsa_exception_int_div_zero 0
	.end_amdhsa_kernel

; __global__ void __launch_bounds__(512, 2) fwd_megakernel(Params p) {
amdhsa.kernels:
  - .agpr_count:     0
    .args:
      - .offset:         0
        .size:           312
        .value_kind:     by_value
      - .offset:         312
        .size:           4
        .value_kind:     hidden_block_count_x
      - .offset:         316
        .size:           4
        .value_kind:     hidden_block_count_y
      - .offset:         320
        .size:           4
        .value_kind:     hidden_block_count_z
      - .offset:         324
        .size:           2
        .value_kind:     hidden_group_size_x
      - .offset:         326
        .size:           2
        .value_kind:     hidden_group_size_y
      - .offset:         328
        .size:           2
        .value_kind:     hidden_group_size_z
      - .offset:         330
        .size:           2
        .value_kind:     hidden_remainder_x
      - .offset:         332
        .size:           2
        .value_kind:     hidden_remainder_y
      - .offset:         334
        .size:           2
        .value_kind:     hidden_remainder_z
      - .offset:         352
        .size:           8
        .value_kind:     hidden_global_offset_x
      - .offset:         360
        .size:           8
        .value_kind:     hidden_global_offset_y
      - .offset:         368
        .size:           8
        .value_kind:     hidden_global_offset_z
      - .offset:         376
        .size:           2
        .value_kind:     hidden_grid_dims
      - .offset:         400
        .size:           8
        .value_kind:     hidden_multigrid_sync_arg
      - .offset:         432
        .size:           4
        .value_kind:     hidden_dynamic_lds_size
    .group_segment_fixed_size: 0
    .kernarg_segment_align: 8
    .kernarg_segment_size: 568
    .language:       OpenCL C
    .language_version:
      - 2
      - 0
    .max_flat_workgroup_size: 512
    .name:           _Z14fwd_megakernel6Params
    .private_segment_fixed_size: 0
    .sgpr_count:     108
    .sgpr_spill_count: 172
    .symbol:         _Z14fwd_megakernel6Params.kd
    .uniform_work_group_size: 1
    .uses_dynamic_stack: false
    .vgpr_count:     256
    .vgpr_spill_count: 0
    .wavefront_size: 64
